# attention partial-O epilogue: 16 dwordx2 stores widened to 8 dwordx4 via v_permlane16_swap pairs (sec 7.3)
# baseline (speedup 1.0000x reference)
; #define GAS __attribute__((address_space(1)))
; DI u32x2 pk4_(const f32x4 v) { u32x2 o; o.x = pk2(v.x, v.y); o.y = pk2(v.z, v.w); return o; }
; DI void u_attn2(Frame& F, int h, int qb, int sp, int ntile) {
;     ...
;     const int slot = att_slot(h, qb, sp);
;     bf16* po = (bf16*)(ws + WS_APO) + (size_t)slot * 32768; float* pm = (float*)(ws + WS_APM) + (size_t)slot * 512;
; #pragma unroll
;     for (int db = 0; db < 8; ++db)
; #pragma unroll
;         for (int qq = 0; qq < 2; ++qq) *(GAS u32x2*)(po + (size_t)(w * 32 + qq * 16 + lc) * 128 + db * 16 + 4 * g4) = pk4_(o[db][qq]);
;     if (g4 == 0) {
; #pragma unroll
;         for (int qq = 0; qq < 2; ++qq) { *(GAS f32x2*)(pm + (w * 32 + qq * 16 + lc) * 2) = (f32x2){mrun[qq], lrun[qq]}; } }
.LBB0_2244:
.LBB0_2245:
	s_or_b64 exec, exec, s[30:31]
	v_mov_b32_e32 v18, v165
	v_mov_b32_e32 v20, v163
	s_nop 0
	v_permlane16_swap_b32 v165, v18
	v_permlane16_swap_b32 v163, v20
	s_nop 0
	v_add_f32_e32 v165, v165, v18
	v_add_f32_e32 v163, v163, v20
	v_mov_b32_e32 v18, v165
	v_mov_b32_e32 v20, v163
	s_nop 0
	v_permlane32_swap_b32 v165, v18
	v_permlane32_swap_b32 v163, v20
	s_nop 0
	v_add_f32_e32 v165, v165, v18
	v_add_f32_e32 v163, v163, v20
	v_lshrrev_b32_e32 v2, 2, v177
	v_add_u32_e32 v4, 1, v2
	v_lshlrev_b32_e32 v2, 1, v2
	v_sub_u32_e32 v2, v177, v2
	v_mul_u32_u24_e32 v3, 0x90, v178
	v_mul_i32_i24_e32 v2, v2, v4
	v_add3_u32 v2, v176, v3, v2
	v_ashrrev_i32_e32 v3, 31, v2
	v_lshlrev_b64 v[4:5], 16, v[2:3]
	v_lshl_add_u64 v[8:9], s[22:23], 0, v[4:5]
	v_or_b32_e32 v4, s42, v161
	v_mov_b32_e32 v161, v19
	v_lshrrev_b32_e32 v6, 3, v160
	v_and_b32_e32 v7, 1, v6
	v_lshrrev_b32_e32 v6, 1, v6
	v_lshlrev_b32_e32 v6, 4, v6
	v_lshl_or_b32 v6, v7, 5, v6
	v_mov_b32_e32 v7, v19
	v_ashrrev_i32_e32 v5, 31, v4
	v_or_b32_e32 v14, 16, v4
	v_lshl_add_u64 v[8:9], v[8:9], 0, v[6:7]
	v_lshlrev_b64 v[12:13], 8, v[4:5]
	v_ashrrev_i32_e32 v15, 31, v14
	v_lshl_add_u64 v[12:13], v[8:9], 0, v[12:13]
	v_lshlrev_b64 v[14:15], 8, v[14:15]
	v_lshl_add_u64 v[8:9], v[8:9], 0, v[14:15]
	v_cvt_pk_bf16_f32 v22, v134, v135
	v_cvt_pk_bf16_f32 v23, v136, v137
	v_cvt_pk_bf16_f32 v24, v106, v107
	v_cvt_pk_bf16_f32 v25, v108, v109
	v_cvt_pk_bf16_f32 v26, v118, v119
	v_cvt_pk_bf16_f32 v27, v120, v121
	v_cvt_pk_bf16_f32 v28, v102, v103
	v_cvt_pk_bf16_f32 v29, v104, v105
	v_cvt_pk_bf16_f32 v30, v98, v99
	v_cvt_pk_bf16_f32 v31, v100, v101
	v_cvt_pk_bf16_f32 v32, v90, v91
	v_cvt_pk_bf16_f32 v33, v92, v93
	v_cvt_pk_bf16_f32 v34, v94, v95
	v_cvt_pk_bf16_f32 v35, v96, v97
	v_cvt_pk_bf16_f32 v36, v86, v87
	v_cvt_pk_bf16_f32 v37, v88, v89
	v_cvt_pk_bf16_f32 v38, v82, v83
	v_cvt_pk_bf16_f32 v39, v84, v85
	v_cvt_pk_bf16_f32 v40, v70, v71
	v_cvt_pk_bf16_f32 v41, v72, v73
	v_cvt_pk_bf16_f32 v42, v78, v79
	v_cvt_pk_bf16_f32 v43, v80, v81
	v_cvt_pk_bf16_f32 v44, v74, v75
	v_cvt_pk_bf16_f32 v45, v76, v77
	v_cvt_pk_bf16_f32 v46, v66, v67
	v_cvt_pk_bf16_f32 v47, v68, v69
	v_cvt_pk_bf16_f32 v48, v54, v55
	v_cvt_pk_bf16_f32 v49, v56, v57
	v_cvt_pk_bf16_f32 v50, v58, v59
	v_cvt_pk_bf16_f32 v51, v60, v61
	v_cvt_pk_bf16_f32 v52, v62, v63
	v_cvt_pk_bf16_f32 v53, v64, v65
	s_nop 1
	v_permlane16_swap_b32 v22, v24
	v_permlane16_swap_b32 v23, v25
	v_permlane16_swap_b32 v26, v28
	v_permlane16_swap_b32 v27, v29
	v_permlane16_swap_b32 v30, v32
	v_permlane16_swap_b32 v31, v33
	v_permlane16_swap_b32 v34, v36
	v_permlane16_swap_b32 v35, v37
	v_permlane16_swap_b32 v38, v40
	v_permlane16_swap_b32 v39, v41
	v_permlane16_swap_b32 v42, v44
	v_permlane16_swap_b32 v43, v45
	v_permlane16_swap_b32 v46, v48
	v_permlane16_swap_b32 v47, v49
	v_permlane16_swap_b32 v50, v52
	v_permlane16_swap_b32 v51, v53
	s_nop 0
	global_store_dwordx4 v[12:13], v[22:25], off
	global_store_dwordx4 v[8:9], v[26:29], off
	global_store_dwordx4 v[12:13], v[30:33], off offset:64
	global_store_dwordx4 v[8:9], v[34:37], off offset:64
	global_store_dwordx4 v[12:13], v[38:41], off offset:128
	global_store_dwordx4 v[8:9], v[42:45], off offset:128
	global_store_dwordx4 v[12:13], v[46:49], off offset:192
	global_store_dwordx4 v[8:9], v[50:53], off offset:192
	v_and_b32_e32 v6, 63, v158
	v_cmp_gt_u32_e32 vcc, 16, v6
	s_and_saveexec_b64 s[30:31], vcc
	v_readlane_b32 s46, v235, 30
	v_readlane_b32 s47, v235, 31
	s_cbranch_execz .LBB0_2230
	v_lshlrev_b64 v[2:3], 11, v[2:3]
	v_lshlrev_b32_e32 v4, 1, v4
	v_lshl_add_u64 v[2:3], s[26:27], 0, v[2:3]
	v_ashrrev_i32_e32 v5, 31, v4
	v_lshl_add_u64 v[2:3], v[4:5], 2, v[2:3]
	global_store_dwordx2 v[2:3], v[164:165], off
	global_store_dwordx2 v[2:3], v[162:163], off offset:128
	s_branch .LBB0_2230
